# scan: dead code removed from producer conversion block (old c1/c2 dot products, w*r, f16 kka/kd) after layout change
# speedup vs baseline: 1.0514x; 1.0094x over previous
.LBB0_61:
	s_cmpk_eq_i32 s4, 0xe040
	s_cbranch_scc1 .LBB0_63
	s_waitcnt vmcnt(0)
	v_cvt_f32_f16_e64 v54, -v12
	v_cvt_f32_f16_sdwa v55, -v12 dst_sel:DWORD dst_unused:UNUSED_PAD src0_sel:WORD_1
	v_cvt_f32_f16_e64 v56, -v13
	v_cvt_f32_f16_sdwa v57, -v13 dst_sel:DWORD dst_unused:UNUSED_PAD src0_sel:WORD_1
	s_waitcnt vmcnt(14)
	v_cvt_f32_f16_e32 v86, v10
	v_cvt_f32_f16_sdwa v87, v10 dst_sel:DWORD dst_unused:UNUSED_PAD src0_sel:WORD_1
	v_cvt_f32_f16_e32 v98, v11
	v_cvt_f32_f16_sdwa v99, v11 dst_sel:DWORD dst_unused:UNUSED_PAD src0_sel:WORD_1
	v_exp_f32_e32 v54, v54
	v_exp_f32_e32 v55, v55
	v_exp_f32_e32 v56, v56
	v_exp_f32_e32 v57, v57
	v_pk_add_f32 v[94:95], v[86:87], -1.0 op_sel_hi:[1,0]
	v_pk_add_f32 v[104:105], v[98:99], -1.0 op_sel_hi:[1,0]
	s_and_b32 s7, s5, 0x10000
	s_lshr_b32 s100, s7, 4
	v_add_u32_e32 v60, s100, v59
	v_lshlrev_b32_e32 v53, 16, v8
	v_and_b32_e32 v81, 0xffff0000, v8
	v_lshlrev_b32_e32 v83, 16, v9
	v_and_b32_e32 v92, 0xffff0000, v9
	v_lshlrev_b32_e32 v88, 16, v6
	v_and_b32_e32 v89, 0xffff0000, v6
	v_pk_fma_f32 v[94:95], v[0:1], v[94:95], 1.0 op_sel_hi:[1,1,0]
	v_lshlrev_b32_e32 v100, 16, v7
	v_and_b32_e32 v101, 0xffff0000, v7
	v_pk_fma_f32 v[104:105], v[2:3], v[104:105], 1.0 op_sel_hi:[1,1,0]
	v_lshlrev_b32_e32 v91, 16, v4
	v_and_b32_e32 v90, 0xffff0000, v4
	v_cvt_pk_f16_f32 v84, v53, v81
	v_mul_f32_e32 v93, v86, v53
	v_pk_mul_f32 v[94:95], v[94:95], v[88:89]
	v_mul_f32_e32 v97, v87, v81
	v_mul_f32_e32 v103, v98, v83
	v_pk_mul_f32 v[100:101], v[104:105], v[100:101]
	v_mul_f32_e32 v81, v99, v92
	v_add_u32_e32 v53, s7, v70
	ds_write_b128 v53, v[54:57]
	ds_write_b32 v53, v93 offset:512
	ds_write_b32 v53, v97 offset:516
	ds_write_b32 v53, v103 offset:520
	ds_write_b32 v53, v81 offset:524
	ds_write_b64 v53, v[94:95] offset:768
	ds_write_b64 v53, v[100:101] offset:776
	v_cvt_pk_f16_f32 v85, v83, v92
	v_and_b32_e32 v88, 0xffff0000, v5
	v_lshlrev_b32_e32 v89, 16, v5
	v_cvt_pk_f16_f32 v86, v91, v90
	v_cvt_pk_f16_f32 v87, v89, v88
	v_lshlrev_b32_e32 v82, 16, v48
	ds_write_b128 v53, v[84:87] offset:256
	s_waitcnt vmcnt(10)
	v_cvt_f32_f16_e32 v86, v24
	v_cvt_f32_f16_sdwa v87, v24 dst_sel:DWORD dst_unused:UNUSED_PAD src0_sel:WORD_1
	v_cvt_f32_f16_e32 v98, v25
	v_cvt_f32_f16_e64 v56, -v27
	v_cvt_f32_f16_sdwa v57, -v27 dst_sel:DWORD dst_unused:UNUSED_PAD src0_sel:WORD_1
	v_cvt_f32_f16_e64 v54, -v26
	v_cvt_f32_f16_sdwa v55, -v26 dst_sel:DWORD dst_unused:UNUSED_PAD src0_sel:WORD_1
	v_cvt_f32_f16_sdwa v99, v25 dst_sel:DWORD dst_unused:UNUSED_PAD src0_sel:WORD_1
	v_exp_f32_e32 v56, v56
	v_exp_f32_e32 v54, v54
	v_exp_f32_e32 v55, v55
	v_exp_f32_e32 v57, v57
	v_pk_add_f32 v[94:95], v[86:87], -1.0 op_sel_hi:[1,0]
	v_pk_add_f32 v[104:105], v[98:99], -1.0 op_sel_hi:[1,0]
	ds_write_b32 v60, v82 offset:0
	v_lshlrev_b32_e32 v81, 16, v22
	v_and_b32_e32 v83, 0xffff0000, v22
	v_lshlrev_b32_e32 v92, 16, v23
	v_and_b32_e32 v96, 0xffff0000, v23
	v_lshlrev_b32_e32 v88, 16, v20
	v_and_b32_e32 v89, 0xffff0000, v20
	v_pk_fma_f32 v[94:95], v[0:1], v[94:95], 1.0 op_sel_hi:[1,1,0]
	v_lshlrev_b32_e32 v100, 16, v21
	v_and_b32_e32 v101, 0xffff0000, v21
	v_pk_fma_f32 v[104:105], v[2:3], v[104:105], 1.0 op_sel_hi:[1,1,0]
	v_lshlrev_b32_e32 v91, 16, v18
	v_and_b32_e32 v90, 0xffff0000, v18
	v_cvt_pk_f16_f32 v84, v81, v83
	v_mul_f32_e32 v93, v86, v81
	v_pk_mul_f32 v[94:95], v[94:95], v[88:89]
	v_mul_f32_e32 v97, v87, v83
	v_mul_f32_e32 v103, v98, v92
	v_pk_mul_f32 v[100:101], v[104:105], v[100:101]
	v_mul_f32_e32 v81, v99, v96
	ds_write_b128 v53, v[54:57] offset:16384
	ds_write_b32 v53, v93 offset:16896
	ds_write_b32 v53, v97 offset:16900
	ds_write_b32 v53, v103 offset:16904
	ds_write_b32 v53, v81 offset:16908
	ds_write_b64 v53, v[94:95] offset:17152
	ds_write_b64 v53, v[100:101] offset:17160
	v_cvt_pk_f16_f32 v85, v92, v96
	v_and_b32_e32 v88, 0xffff0000, v19
	v_lshlrev_b32_e32 v89, 16, v19
	v_cvt_pk_f16_f32 v86, v91, v90
	v_cvt_pk_f16_f32 v87, v89, v88
	v_lshlrev_b32_e32 v82, 16, v49
	ds_write_b128 v53, v[84:87] offset:16640
	s_waitcnt vmcnt(6)
	v_cvt_f32_f16_e32 v86, v34
	v_cvt_f32_f16_sdwa v87, v34 dst_sel:DWORD dst_unused:UNUSED_PAD src0_sel:WORD_1
	v_cvt_f32_f16_e32 v98, v35
	v_cvt_f32_f16_e64 v56, -v37
	v_cvt_f32_f16_sdwa v57, -v37 dst_sel:DWORD dst_unused:UNUSED_PAD src0_sel:WORD_1
	v_cvt_f32_f16_e64 v54, -v36
	v_cvt_f32_f16_sdwa v55, -v36 dst_sel:DWORD dst_unused:UNUSED_PAD src0_sel:WORD_1
	v_cvt_f32_f16_sdwa v99, v35 dst_sel:DWORD dst_unused:UNUSED_PAD src0_sel:WORD_1
	v_exp_f32_e32 v56, v56
	v_exp_f32_e32 v54, v54
	v_exp_f32_e32 v55, v55
	v_exp_f32_e32 v57, v57
	v_pk_add_f32 v[94:95], v[86:87], -1.0 op_sel_hi:[1,0]
	v_pk_add_f32 v[104:105], v[98:99], -1.0 op_sel_hi:[1,0]
	ds_write_b32 v60, v82 offset:1024
	v_lshlrev_b32_e32 v81, 16, v32
	v_and_b32_e32 v83, 0xffff0000, v32
	v_lshlrev_b32_e32 v92, 16, v33
	v_and_b32_e32 v96, 0xffff0000, v33
	v_lshlrev_b32_e32 v88, 16, v30
	v_and_b32_e32 v89, 0xffff0000, v30
	v_pk_fma_f32 v[94:95], v[0:1], v[94:95], 1.0 op_sel_hi:[1,1,0]
	v_lshlrev_b32_e32 v100, 16, v31
	v_and_b32_e32 v101, 0xffff0000, v31
	v_pk_fma_f32 v[104:105], v[2:3], v[104:105], 1.0 op_sel_hi:[1,1,0]
	v_lshlrev_b32_e32 v91, 16, v28
	v_and_b32_e32 v90, 0xffff0000, v28
	v_cvt_pk_f16_f32 v84, v81, v83
	v_mul_f32_e32 v93, v86, v81
	v_pk_mul_f32 v[94:95], v[94:95], v[88:89]
	v_mul_f32_e32 v97, v87, v83
	v_mul_f32_e32 v103, v98, v92
	v_pk_mul_f32 v[100:101], v[104:105], v[100:101]
	v_mul_f32_e32 v81, v99, v96
	ds_write_b128 v53, v[54:57] offset:32768
	ds_write_b32 v53, v93 offset:33280
	ds_write_b32 v53, v97 offset:33284
	ds_write_b32 v53, v103 offset:33288
	ds_write_b32 v53, v81 offset:33292
	ds_write_b64 v53, v[94:95] offset:33536
	ds_write_b64 v53, v[100:101] offset:33544
	v_cvt_pk_f16_f32 v85, v92, v96
	v_and_b32_e32 v88, 0xffff0000, v29
	v_lshlrev_b32_e32 v89, 16, v29
	v_cvt_pk_f16_f32 v86, v91, v90
	v_cvt_pk_f16_f32 v87, v89, v88
	v_lshlrev_b32_e32 v82, 16, v50
	ds_write_b128 v53, v[84:87] offset:33024
	s_waitcnt vmcnt(2)
	v_cvt_f32_f16_e32 v86, v44
	v_cvt_f32_f16_sdwa v87, v44 dst_sel:DWORD dst_unused:UNUSED_PAD src0_sel:WORD_1
	v_cvt_f32_f16_e32 v98, v45
	s_waitcnt vmcnt(1)
	v_cvt_f32_f16_e64 v56, -v47
	v_cvt_f32_f16_sdwa v57, -v47 dst_sel:DWORD dst_unused:UNUSED_PAD src0_sel:WORD_1
	v_cvt_f32_f16_e64 v54, -v46
	v_cvt_f32_f16_sdwa v55, -v46 dst_sel:DWORD dst_unused:UNUSED_PAD src0_sel:WORD_1
	v_cvt_f32_f16_sdwa v99, v45 dst_sel:DWORD dst_unused:UNUSED_PAD src0_sel:WORD_1
	v_exp_f32_e32 v56, v56
	v_exp_f32_e32 v54, v54
	v_exp_f32_e32 v55, v55
	v_exp_f32_e32 v57, v57
	v_pk_add_f32 v[94:95], v[86:87], -1.0 op_sel_hi:[1,0]
	v_pk_add_f32 v[104:105], v[98:99], -1.0 op_sel_hi:[1,0]
	ds_write_b32 v60, v82 offset:2048
	v_lshlrev_b32_e32 v81, 16, v42
	v_and_b32_e32 v83, 0xffff0000, v42
	v_lshlrev_b32_e32 v92, 16, v43
	v_and_b32_e32 v96, 0xffff0000, v43
	v_lshlrev_b32_e32 v88, 16, v40
	v_and_b32_e32 v89, 0xffff0000, v40
	v_pk_fma_f32 v[94:95], v[0:1], v[94:95], 1.0 op_sel_hi:[1,1,0]
	v_lshlrev_b32_e32 v100, 16, v41
	v_and_b32_e32 v101, 0xffff0000, v41
	v_pk_fma_f32 v[104:105], v[2:3], v[104:105], 1.0 op_sel_hi:[1,1,0]
	v_lshlrev_b32_e32 v91, 16, v38
	v_and_b32_e32 v90, 0xffff0000, v38
	v_cvt_pk_f16_f32 v84, v81, v83
	v_mul_f32_e32 v93, v86, v81
	v_pk_mul_f32 v[94:95], v[94:95], v[88:89]
	v_mul_f32_e32 v97, v87, v83
	v_mul_f32_e32 v103, v98, v92
	v_pk_mul_f32 v[100:101], v[104:105], v[100:101]
	v_mul_f32_e32 v81, v99, v96
	ds_write_b128 v53, v[54:57] offset:49152
	ds_write_b32 v53, v93 offset:49664
	ds_write_b32 v53, v97 offset:49668
	ds_write_b32 v53, v103 offset:49672
	ds_write_b32 v53, v81 offset:49676
	ds_write_b64 v53, v[94:95] offset:49920
	ds_write_b64 v53, v[100:101] offset:49928
	v_cvt_pk_f16_f32 v85, v92, v96
	v_and_b32_e32 v88, 0xffff0000, v39
	v_lshlrev_b32_e32 v89, 16, v39
	v_cvt_pk_f16_f32 v86, v91, v90
	v_cvt_pk_f16_f32 v87, v89, v88
	s_waitcnt vmcnt(0)
	v_lshlrev_b32_e32 v82, 16, v51
	ds_write_b128 v53, v[84:87] offset:49408
	s_nop 0
	s_nop 0
	s_nop 0
	s_nop 0
	ds_write_b32 v60, v82 offset:3072
